# v15 plus MLA attention role swap: older waves 0-3 take the deferred-PV role, younger waves 4-7 the immediate-PV role
# speedup vs baseline: 1.0093x; 1.0001x over previous
; #define LAS __attribute__((address_space(3)))
; template <int DQK, int MODE>
; DEVI void attn_item(LAS unsigned char* lds, const bf16_t* Qh, int qs, const bf16_t* Kh, int ks_, const bf16_t* Vh, int vs, bf16_t* Oh, int os,
;                     float* lse, int lses, int i0, int dil, int res) {
;     ...
;     const int tid = otid(), wave = tid >> 6, lane = tid & 63, l31 = lane & 31, hh = lane >> 5;
;     const bool grpB = __builtin_amdgcn_readfirstlane(wave) >= 4;
;     const int qidx = i0 + 32 * wave + l31;
;     bf16x8 qf[DQK / 16];
;     { const bf16_t* qrow = Qh + (size_t)(res + dil * qidx) * qs;
; #pragma unroll
;       for (int k = 0; k < DQK / 16; ++k) qf[k] = *(const bf16x8*)(qrow + 16 * k + 8 * hh);
; #pragma unroll
;       for (int k = 0; k < DQK / 16; ++k) asm volatile("" : "+v"(qf[k]));
;     }
;     const int kbase = MODE ? (i0 - 128) : 0;
;     const int j0 = (MODE && kbase < 0) ? 2 : 0;
;     const int j1 = MODE ? 6 : (i0 / 64 + 4);
;     f32x16 O[4];
; #pragma unroll
;     for (int c = 0; c < 4; ++c)
; #pragma unroll
;         for (int j = 0; j < 16; ++j) O[c][j] = 0.f;
;     float mrun = -1e30f, lrun = 0.f;
;     u32x4 kreg[C::NKC], vreg[2];
;     u32x4 pk[4];
; #pragma unroll
;     for (int i = 0; i < 4; ++i) pk[i] = (u32x4){0u, 0u, 0u, 0u};
;     auto gload = [&](int jt) {
;         const int kb0 = kbase + 64 * jt;
; #pragma unroll
;         for (int u = 0; u < C::NKC; ++u) { const int id = tid + NT * u, row = id / (DQK / 8), cc = id % (DQK / 8);
;             kreg[u] = *(const u32x4*)(Kh + (size_t)(res + dil * (kb0 + row)) * ks_ + cc * 8); }
; #pragma unroll
;         for (int u = 0; u < 2; ++u) { const int id = tid + NT * u, row = id >> 4, cc = id & 15;
;             vreg[u] = *(const u32x4*)(Vh + (size_t)(res + dil * (kb0 + row)) * vs + cc * 8); }
;     };
;     auto lstore = [&](int kbi, int vbi) {
;         LAS unsigned char* kb_ = lds + kbi * C::KB; LAS unsigned char* vb_ = lds + C::VOFF + vbi * C::VB;
; #pragma unroll
; DEVI void emix(LAS unsigned char* lds, const Params& P) {
;     ...
;         __syncthreads();
;         const int head = slot[0], n = slot[1];
;         __syncthreads();
;         if (head < 0) break;
;         const int qb = 63 - n;
;         attn_item<192, 0>(lds, Q + head * 192, 1536, Km + head * 192, 1536, kv + head * 256 + 128, 2048, mix + head * 128, 2048, nullptr, 0, qb * 256, 1, 0);
.LBB0_1091:
	s_or_b64 exec, exec, s[14:15]
	s_waitcnt lgkmcnt(0)
	s_barrier
	ds_read_b64 v[2:3], v192
	s_waitcnt lgkmcnt(0)
	s_barrier
	v_readfirstlane_b32 s31, v2
	v_readfirstlane_b32 s14, v3
	s_cmp_lt_i32 s31, 0
	s_cbranch_scc1 .LBB0_1108
	s_mul_i32 s0, s31, 0xc0
	s_lshl_b64 s[16:17], s[0:1], 1
	s_add_u32 s50, s4, s16
	s_addc_u32 s51, s5, s17
	s_add_u32 s16, s6, s16
	s_addc_u32 s17, s7, s17
	s_lshl_b32 s0, s31, 8
	s_lshl_b64 s[72:73], s[0:1], 1
	v_readlane_b32 s76, v239, 0
	v_readlane_b32 s77, v239, 1
	s_add_u32 s0, s76, s72
	v_readlane_b32 s80, v239, 4
	s_addc_u32 s15, s77, s73
	v_readlane_b32 s81, v239, 5
	s_add_u32 s80, s0, 0x20ec4500
	s_addc_u32 s81, s15, 0
	s_lshl_b32 s0, s14, 8
	s_waitcnt vmcnt(17)
	v_mov_b32_e32 v22, v196
	s_sub_i32 s0, 0x3f00, s0
	v_mov_b64_e32 v[2:3], s[50:51]
	v_ashrrev_i32_e32 v23, 6, v22
	v_and_b32_e32 v14, 31, v22
	v_lshl_add_u32 v202, v23, 5, s0
	v_bfe_u32 v194, v22, 5, 1
	v_or_b32_e32 v180, v202, v14
	v_mad_i64_i32 v[4:5], s[14:15], v180, s27, v[2:3]
	v_lshlrev_b32_e32 v2, 4, v194
	v_mov_b32_e32 v3, v1
	v_lshl_add_u64 v[4:5], v[4:5], 0, v[2:3]
	global_load_dwordx4 v[112:115], v[4:5], off
	global_load_dwordx4 v[116:119], v[4:5], off offset:32
	global_load_dwordx4 v[120:123], v[4:5], off offset:64
	global_load_dwordx4 v[124:127], v[4:5], off offset:96
	global_load_dwordx4 v[128:131], v[4:5], off offset:128
	global_load_dwordx4 v[132:135], v[4:5], off offset:160
	global_load_dwordx4 v[136:139], v[4:5], off offset:192
	global_load_dwordx4 v[140:143], v[4:5], off offset:224
	global_load_dwordx4 v[144:147], v[4:5], off offset:256
	global_load_dwordx4 v[148:151], v[4:5], off offset:288
	global_load_dwordx4 v[152:155], v[4:5], off offset:320
	global_load_dwordx4 v[156:159], v[4:5], off offset:352
	v_mul_hi_i32 v0, v22, s28
	s_waitcnt vmcnt(28)
	v_add_u32_e32 v24, 0x200, v22
	v_add_u32_e32 v7, 0x400, v22
	v_ashrrev_i32_e32 v4, 4, v22
	v_lshlrev_b32_e32 v3, 3, v22
	v_lshrrev_b32_e32 v6, 31, v0
	v_ashrrev_i32_e32 v0, 2, v0
	v_mul_hi_i32 v8, v24, s28
	v_mul_hi_i32 v9, v7, s28
	v_ashrrev_i32_e32 v5, 31, v4
	v_and_b32_e32 v10, 0x78, v3
	v_add_u32_e32 v3, v0, v6
	v_lshrrev_b32_e32 v6, 31, v8
	v_ashrrev_i32_e32 v8, 2, v8
	v_lshrrev_b32_e32 v11, 31, v9
	v_ashrrev_i32_e32 v9, 2, v9
	v_lshlrev_b64 v[12:13], 12, v[4:5]
	v_lshlrev_b32_e32 v0, 1, v10
	v_mul_lo_u32 v10, v3, 24
	v_add_u32_e32 v5, v8, v6
	v_add_u32_e32 v15, v9, v11
	v_sub_u32_e32 v25, v22, v10
	v_mul_lo_u32 v10, v5, 24
	v_mul_lo_u32 v11, v15, 24
	v_mov_b64_e32 v[8:9], s[16:17]
	v_lshlrev_b32_e32 v6, 3, v25
	v_sub_u32_e32 v26, v24, v10
	v_sub_u32_e32 v27, v7, v11
	v_mad_i64_i32 v[16:17], s[14:15], v3, s27, v[8:9]
	v_mad_i64_i32 v[18:19], s[14:15], v5, s27, v[8:9]
	v_mad_i64_i32 v[20:21], s[14:15], v15, s27, v[8:9]
	v_ashrrev_i32_e32 v7, 31, v6
	v_lshlrev_b32_e32 v8, 3, v26
	v_lshlrev_b32_e32 v10, 3, v27
	v_lshl_add_u64 v[12:13], s[80:81], 0, v[12:13]
	v_lshl_add_u64 v[16:17], v[6:7], 1, v[16:17]
	v_ashrrev_i32_e32 v9, 31, v8
	v_ashrrev_i32_e32 v11, 31, v10
	v_lshl_add_u64 v[12:13], v[12:13], 0, v[0:1]
	v_lshl_add_u64 v[18:19], v[8:9], 1, v[18:19]
	v_lshl_add_u64 v[20:21], v[10:11], 1, v[20:21]
	v_readfirstlane_b32 s35, v23
	s_cmp_lt_i32 s35, 4
	v_readlane_b32 s82, v239, 6
	v_readlane_b32 s83, v239, 7
	v_mul_lo_u32 v206, v3, s29
	v_lshlrev_b32_e32 v209, 4, v25
	s_cselect_b64 s[14:15], -1, 0
	s_cmp_gt_i32 s35, 3
	v_bfe_u32 v199, v22, 2, 2
	s_waitcnt vmcnt(11)
	s_waitcnt vmcnt(10)
	s_waitcnt vmcnt(9)
	s_waitcnt vmcnt(8)
	s_waitcnt vmcnt(7)
	s_waitcnt vmcnt(6)
	s_waitcnt vmcnt(5)
	s_waitcnt vmcnt(4)
	s_waitcnt vmcnt(3)
	s_waitcnt vmcnt(2)
	s_waitcnt vmcnt(1)
	s_waitcnt vmcnt(0)
	global_load_dwordx4 v[160:163], v[16:17], off
	global_load_dwordx4 v[164:167], v[18:19], off
	global_load_dwordx4 v[168:171], v[20:21], off
	global_load_dwordx4 v[172:175], v[12:13], off
	v_ashrrev_i32_e32 v12, 4, v24
	v_ashrrev_i32_e32 v13, 31, v12
	v_lshlrev_b64 v[16:17], 12, v[12:13]
	v_lshl_add_u64 v[16:17], s[80:81], 0, v[16:17]
	v_lshl_add_u64 v[16:17], v[16:17], 0, v[0:1]
	global_load_dwordx4 v[176:179], v[16:17], off
	v_and_b32_e32 v13, 3, v22
	v_bfe_u32 v16, v22, 4, 1
	v_lshlrev_b32_e32 v17, 4, v22
	v_mul_lo_u32 v203, v4, s34
	v_and_b32_e32 v204, 0xf0, v17
	v_lshlrev_b32_e32 v200, 3, v13
	v_lshlrev_b32_e32 v201, 5, v16
	v_mul_lo_u32 v205, v12, s34
	v_mul_lo_u32 v207, v5, s29
	v_mul_lo_u32 v208, v15, s29
	v_add3_u32 v17, 0, v206, v209
	v_lshlrev_b32_e32 v210, 4, v26
	v_lshlrev_b32_e32 v211, 4, v27
	v_ashrrev_i32_e32 v181, 31, v180
	s_cselect_b64 s[82:83], -1, 0
	s_cmpk_lt_i32 s0, 0xff01
	v_lshlrev_b32_e32 v195, 2, v194
	v_readlane_b32 s78, v239, 2
	v_readlane_b32 s79, v239, 3
	v_add3_u32 v13, 0, v203, v204
	v_add3_u32 v16, 0, v205, v204
	v_add3_u32 v18, 0, v207, v210
	v_add3_u32 v19, 0, v208, v211
	s_waitcnt vmcnt(4)
	ds_write_b128 v17, v[160:163]
	s_waitcnt vmcnt(3)
	ds_write_b128 v18, v[164:167]
	s_waitcnt vmcnt(2)
	ds_write_b128 v19, v[168:171]
	s_waitcnt vmcnt(1)
	ds_write_b128 v13, v[172:175] offset:51200
	s_waitcnt vmcnt(0)
	ds_write_b128 v16, v[176:179] offset:51200
	s_waitcnt lgkmcnt(0)
	s_barrier
; template <int DQK, int MODE>
; DEVI void attn_item(LAS unsigned char* lds, const bf16_t* Qh, int qs, const bf16_t* Kh, int ks_, const bf16_t* Vh, int vs, bf16_t* Oh, int os,
;                     float* lse, int lses, int i0, int dil, int res) {
;     ...
;     const int kbase = MODE ? (i0 - 128) : 0;
;     const int j0 = (MODE && kbase < 0) ? 2 : 0;
;     const int j1 = MODE ? 6 : (i0 / 64 + 4);
;     f32x16 O[4];
; #pragma unroll
;     for (int c = 0; c < 4; ++c)
; #pragma unroll
;         for (int j = 0; j < 16; ++j) O[c][j] = 0.f;
;     float mrun = -1e30f, lrun = 0.f;
;     u32x4 kreg[C::NKC], vreg[2];
;     u32x4 pk[4];
; #pragma unroll
;     for (int i = 0; i < 4; ++i) pk[i] = (u32x4){0u, 0u, 0u, 0u};
;     ...
;     const int qw0 = i0 + 32 * wave;
;     bool havePrev = false;
;     int kbi = 0, vbi = 0;
;     for (int jt = j0; jt < j1; ++jt) {
	s_cbranch_scc1 .LBB0_1109
	v_lshlrev_b32_e32 v212, 2, v194
	v_lshl_add_u64 v[188:189], s[80:81], 0, v[0:1]
	v_or_b32_e32 v0, v212, v199
	v_mad_u32_u24 v0, v0, s34, 0
	s_ashr_i32 s35, s0, 6
	v_add3_u32 v213, v0, v201, v200
	v_mul_u32_u24_e32 v0, 0x190, v14
	v_add_u32_e32 v218, 64, v15
	v_mov_b32_e32 v14, v1
	v_mov_b32_e32 v15, v1
	s_add_i32 s35, s35, 4
	v_lshl_add_u64 v[182:183], v[6:7], 1, s[16:17]
	v_lshl_add_u64 v[184:185], v[8:9], 1, s[16:17]
	v_lshl_add_u64 v[186:187], v[10:11], 1, s[16:17]
	v_add3_u32 v215, 0, v0, v2
	v_add_u32_e32 v216, 64, v12
	v_add_u32_e32 v217, 64, v4
	v_add_u32_e32 v219, 64, v5
	v_add_u32_e32 v220, 64, v3
	v_mov_b32_e32 v0, v1
	v_mov_b32_e32 v2, v1
	v_mov_b32_e32 v3, v1
	v_mov_b32_e32 v4, v1
	v_mov_b32_e32 v5, v1
	v_mov_b32_e32 v6, v1
	v_mov_b32_e32 v7, v1
	v_mov_b32_e32 v8, v1
	v_mov_b32_e32 v9, v1
	v_mov_b32_e32 v10, v1
	v_mov_b32_e32 v11, v1
	v_mov_b32_e32 v12, v1
	v_mov_b32_e32 v13, v1
	v_mov_b64_e32 v[30:31], v[14:15]
	v_mov_b64_e32 v[46:47], v[14:15]
	v_mov_b64_e32 v[62:63], v[14:15]
	v_mov_b64_e32 v[78:79], v[14:15]
	v_readlane_b32 s78, v240, 54
	v_or_b32_e32 v214, 31, v202
	s_max_i32 s49, s35, 1
	s_mov_b32 s50, 0
	s_mov_b64 s[80:81], 0
	v_mov_b32_e32 v190, 0xf149f2ca
	v_mov_b32_e32 v198, 0
	v_mov_b32_e32 v80, 0
	v_mov_b32_e32 v81, 0
	v_mov_b32_e32 v82, 0
	v_mov_b32_e32 v83, 0
	v_mov_b32_e32 v84, 0
	v_mov_b32_e32 v85, 0
	v_mov_b32_e32 v86, 0
	v_mov_b32_e32 v87, 0
	v_mov_b32_e32 v88, 0
	v_mov_b32_e32 v89, 0
	v_mov_b32_e32 v90, 0
	v_mov_b32_e32 v91, 0
	v_mov_b32_e32 v92, 0
	v_mov_b32_e32 v93, 0
	v_mov_b32_e32 v94, 0
	v_mov_b32_e32 v95, 0
	v_mov_b64_e32 v[28:29], v[12:13]
	v_mov_b64_e32 v[26:27], v[10:11]
	v_mov_b64_e32 v[24:25], v[8:9]
	v_mov_b64_e32 v[22:23], v[6:7]
	v_mov_b64_e32 v[20:21], v[4:5]
	v_mov_b64_e32 v[18:19], v[2:3]
	v_mov_b64_e32 v[16:17], v[0:1]
	v_mov_b64_e32 v[44:45], v[12:13]
	v_mov_b64_e32 v[42:43], v[10:11]
	v_mov_b64_e32 v[40:41], v[8:9]
	v_mov_b64_e32 v[38:39], v[6:7]
	v_mov_b64_e32 v[36:37], v[4:5]
	v_mov_b64_e32 v[34:35], v[2:3]
	v_mov_b64_e32 v[32:33], v[0:1]
	v_mov_b64_e32 v[60:61], v[12:13]
	v_mov_b64_e32 v[58:59], v[10:11]
	v_mov_b64_e32 v[56:57], v[8:9]
	v_mov_b64_e32 v[54:55], v[6:7]
	v_mov_b64_e32 v[52:53], v[4:5]
	v_mov_b64_e32 v[50:51], v[2:3]
	v_mov_b64_e32 v[48:49], v[0:1]
	v_mov_b64_e32 v[76:77], v[12:13]
	v_mov_b64_e32 v[74:75], v[10:11]
	v_mov_b64_e32 v[72:73], v[8:9]
	v_mov_b64_e32 v[70:71], v[6:7]
	v_mov_b64_e32 v[68:69], v[4:5]
	v_mov_b64_e32 v[66:67], v[2:3]
	v_mov_b64_e32 v[64:65], v[0:1]
	s_mov_b32 s51, 0
	s_mov_b32 s0, 0
	s_mov_b32 s72, 0
	v_readlane_b32 s79, v240, 55
	s_branch .LBB0_1095
